# grid barrier: acquire L1 invalidate issued at arrival instead of after the release is observed; plus silu batch, transposed epilogue stores, rowwise-mid fix
# speedup vs baseline: 1.0332x; 1.0332x over previous
; __device__ __forceinline__ unsigned xb_ld(unsigned* p)              { return __hip_atomic_load(p, __ATOMIC_RELAXED, __HIP_MEMORY_SCOPE_AGENT); }
; __device__ __forceinline__ unsigned xb_add(unsigned* p, unsigned v) { return __hip_atomic_fetch_add(p, v, __ATOMIC_RELAXED, __HIP_MEMORY_SCOPE_AGENT); }
; #define XB_SPIN(cond, bar) do { unsigned _sp = 0; while (cond) { __builtin_amdgcn_s_sleep(1); \
;     if ((++_sp & 255u) == 0u) { if (xb_ld(&(bar)[XB_TMO])) break; if (_sp > XB_SPIN_CAP) { atomicAdd(&(bar)[XB_TMO], 1u); break; } } } } while (0)
; __device__ __forceinline__ void xcd_barrier(const XcdBarrier& b) {
;     ...
;         unsigned nloc = b.st[0], nx = b.st[1];
;         if (nloc == 0u) { xcd_barrier_complete(bar, b.x, nloc, nx); b.st[0] = nloc; b.st[1] = nx; }
;         const unsigned old = xb_add(&bar[XB_XSUB(b.x)], 1u);
;         const unsigned gen = old / nloc;
;         if (old + 1u == (gen + 1u) * nloc) {
;             __builtin_amdgcn_fence(__ATOMIC_RELEASE, "agent");
;             asm volatile("s_waitcnt vmcnt(0)" ::: "memory");
;             const unsigned og = xb_add(&bar[XB_TOP], 1u);
;             const unsigned tg = og / nx;
;             if (og + 1u == (tg + 1u) * nx) xb_add(&bar[XB_TOPGEN], 1u);
;             else XB_SPIN(xb_ld(&bar[XB_TOPGEN]) == tg, bar);
;             __builtin_amdgcn_fence(__ATOMIC_ACQUIRE, "agent");
;             xb_add(&bar[XB_XGEN(b.x)], 1u);
;             asm volatile("s_waitcnt vmcnt(0)" ::: "memory");
;         } else {
;             XB_SPIN(xb_ld(&bar[XB_XGEN(b.x)]) == gen, bar);
.LBB0_66:
	s_or_b64 exec, exec, s[14:15]
	buffer_inv sc1
	v_cvt_f32_u32_e32 v4, v2
	s_waitcnt vmcnt(1)
	v_readfirstlane_b32 s4, v3
	v_sub_u32_e32 v3, 0, v2
	v_rcp_iflag_f32_e32 v4, v4
	v_add_u32_e32 v5, s4, v1
	v_mul_f32_e32 v4, 0x4f7ffffe, v4
	v_cvt_u32_f32_e32 v4, v4
	v_mul_lo_u32 v1, v3, v4
	v_mul_hi_u32 v1, v4, v1
	v_add_u32_e32 v1, v4, v1
	v_mul_hi_u32 v1, v5, v1
	v_mul_lo_u32 v3, v1, v2
	v_sub_u32_e32 v3, v5, v3
	v_add_u32_e32 v4, 1, v1
	v_cmp_ge_u32_e32 vcc, v3, v2
	s_nop 1
	v_cndmask_b32_e32 v1, v1, v4, vcc
	v_sub_u32_e32 v4, v3, v2
	v_cndmask_b32_e32 v3, v3, v4, vcc
	v_add_u32_e32 v4, 1, v1
	v_cmp_ge_u32_e32 vcc, v3, v2
	v_add_u32_e32 v3, 1, v5
	s_nop 0
	v_cndmask_b32_e32 v1, v1, v4, vcc
	v_mul_lo_u32 v4, v2, v1
	v_add_u32_e32 v2, v4, v2
	v_cmp_ne_u32_e32 vcc, v3, v2
	s_and_saveexec_b64 s[4:5], vcc
	s_xor_b64 s[14:15], exec, s[4:5]
	s_cbranch_execz .LBB0_80
	v_readlane_b32 s4, v245, 18
	s_waitcnt lgkmcnt(0)
	v_mov_b32_e32 v0, 0
	v_readlane_b32 s5, v245, 19
	s_nop 4
	global_load_dword v2, v0, s[4:5] sc1
	s_waitcnt vmcnt(0)
	v_cmp_eq_u32_e32 vcc, v2, v1
	s_and_saveexec_b64 s[18:19], vcc
	s_cbranch_execz .LBB0_79
	s_mov_b32 s4, 1
	s_mov_b64 s[20:21], 0
	s_branch .LBB0_70

; __device__ __forceinline__ unsigned xb_ld(unsigned* p)              { return __hip_atomic_load(p, __ATOMIC_RELAXED, __HIP_MEMORY_SCOPE_AGENT); }
; __device__ __forceinline__ unsigned xb_add(unsigned* p, unsigned v) { return __hip_atomic_fetch_add(p, v, __ATOMIC_RELAXED, __HIP_MEMORY_SCOPE_AGENT); }
; #define XB_SPIN(cond, bar) do { unsigned _sp = 0; while (cond) { __builtin_amdgcn_s_sleep(1); \
;     if ((++_sp & 255u) == 0u) { if (xb_ld(&(bar)[XB_TMO])) break; if (_sp > XB_SPIN_CAP) { atomicAdd(&(bar)[XB_TMO], 1u); break; } } } } while (0)
; __device__ __forceinline__ void xcd_barrier(const XcdBarrier& b) {
;     ...
;         unsigned nloc = b.st[0], nx = b.st[1];
;         if (nloc == 0u) { xcd_barrier_complete(bar, b.x, nloc, nx); b.st[0] = nloc; b.st[1] = nx; }
;         const unsigned old = xb_add(&bar[XB_XSUB(b.x)], 1u);
;         const unsigned gen = old / nloc;
;         if (old + 1u == (gen + 1u) * nloc) {
;             __builtin_amdgcn_fence(__ATOMIC_RELEASE, "agent");
;             asm volatile("s_waitcnt vmcnt(0)" ::: "memory");
;             const unsigned og = xb_add(&bar[XB_TOP], 1u);
;             const unsigned tg = og / nx;
;             if (og + 1u == (tg + 1u) * nx) xb_add(&bar[XB_TOPGEN], 1u);
;             else XB_SPIN(xb_ld(&bar[XB_TOPGEN]) == tg, bar);
;             __builtin_amdgcn_fence(__ATOMIC_ACQUIRE, "agent");
;             xb_add(&bar[XB_XGEN(b.x)], 1u);
;             asm volatile("s_waitcnt vmcnt(0)" ::: "memory");
;         } else {
;             XB_SPIN(xb_ld(&bar[XB_XGEN(b.x)]) == gen, bar);
.LBB0_139:
	s_or_b64 exec, exec, s[8:9]
	buffer_inv sc1
	v_cvt_f32_u32_e32 v4, v2
	s_waitcnt vmcnt(1)
	v_readfirstlane_b32 s3, v3
	v_sub_u32_e32 v3, 0, v2
	v_rcp_iflag_f32_e32 v4, v4
	v_add_u32_e32 v5, s3, v1
	v_mul_f32_e32 v4, 0x4f7ffffe, v4
	v_cvt_u32_f32_e32 v4, v4
	v_mul_lo_u32 v1, v3, v4
	v_mul_hi_u32 v1, v4, v1
	v_add_u32_e32 v1, v4, v1
	v_mul_hi_u32 v1, v5, v1
	v_mul_lo_u32 v3, v1, v2
	v_sub_u32_e32 v3, v5, v3
	v_add_u32_e32 v4, 1, v1
	v_cmp_ge_u32_e32 vcc, v3, v2
	s_nop 1
	v_cndmask_b32_e32 v1, v1, v4, vcc
	v_sub_u32_e32 v4, v3, v2
	v_cndmask_b32_e32 v3, v3, v4, vcc
	v_add_u32_e32 v4, 1, v1
	v_cmp_ge_u32_e32 vcc, v3, v2
	v_add_u32_e32 v3, 1, v5
	s_nop 0
	v_cndmask_b32_e32 v1, v1, v4, vcc
	v_mul_lo_u32 v4, v2, v1
	v_add_u32_e32 v2, v4, v2
	v_cmp_ne_u32_e32 vcc, v3, v2
	s_and_saveexec_b64 s[4:5], vcc
	s_xor_b64 s[8:9], exec, s[4:5]
	s_cbranch_execz .LBB0_153
	v_readlane_b32 s4, v245, 18
	s_waitcnt lgkmcnt(0)
	v_mov_b32_e32 v0, 0
	v_readlane_b32 s5, v245, 19
	s_nop 4
	global_load_dword v2, v0, s[4:5] sc1
	s_waitcnt vmcnt(0)
	v_cmp_eq_u32_e32 vcc, v2, v1
	s_and_saveexec_b64 s[14:15], vcc
	s_cbranch_execz .LBB0_152
	s_mov_b32 s3, 1
	s_mov_b64 s[18:19], 0
	s_branch .LBB0_143

; __device__ __forceinline__ unsigned xb_ld(unsigned* p)              { return __hip_atomic_load(p, __ATOMIC_RELAXED, __HIP_MEMORY_SCOPE_AGENT); }
; __device__ __forceinline__ unsigned xb_add(unsigned* p, unsigned v) { return __hip_atomic_fetch_add(p, v, __ATOMIC_RELAXED, __HIP_MEMORY_SCOPE_AGENT); }
; #define XB_SPIN(cond, bar) do { unsigned _sp = 0; while (cond) { __builtin_amdgcn_s_sleep(1); \
;     if ((++_sp & 255u) == 0u) { if (xb_ld(&(bar)[XB_TMO])) break; if (_sp > XB_SPIN_CAP) { atomicAdd(&(bar)[XB_TMO], 1u); break; } } } } while (0)
; __device__ __forceinline__ void xcd_barrier(const XcdBarrier& b) {
;     ...
;         unsigned nloc = b.st[0], nx = b.st[1];
;         if (nloc == 0u) { xcd_barrier_complete(bar, b.x, nloc, nx); b.st[0] = nloc; b.st[1] = nx; }
;         const unsigned old = xb_add(&bar[XB_XSUB(b.x)], 1u);
;         const unsigned gen = old / nloc;
;         if (old + 1u == (gen + 1u) * nloc) {
;             __builtin_amdgcn_fence(__ATOMIC_RELEASE, "agent");
;             asm volatile("s_waitcnt vmcnt(0)" ::: "memory");
;             const unsigned og = xb_add(&bar[XB_TOP], 1u);
;             const unsigned tg = og / nx;
;             if (og + 1u == (tg + 1u) * nx) xb_add(&bar[XB_TOPGEN], 1u);
;             else XB_SPIN(xb_ld(&bar[XB_TOPGEN]) == tg, bar);
;             __builtin_amdgcn_fence(__ATOMIC_ACQUIRE, "agent");
;             xb_add(&bar[XB_XGEN(b.x)], 1u);
;             asm volatile("s_waitcnt vmcnt(0)" ::: "memory");
;         } else {
;             XB_SPIN(xb_ld(&bar[XB_XGEN(b.x)]) == gen, bar);
.LBB0_227:
	s_or_b64 exec, exec, s[16:17]
	buffer_inv sc1
	v_cvt_f32_u32_e32 v5, v3
	s_waitcnt vmcnt(1)
	v_readfirstlane_b32 s16, v4
	v_sub_u32_e32 v4, 0, v3
	v_rcp_iflag_f32_e32 v5, v5
	v_add_u32_e32 v6, s16, v0
	v_mul_f32_e32 v5, 0x4f7ffffe, v5
	v_cvt_u32_f32_e32 v5, v5
	v_mul_lo_u32 v0, v4, v5
	v_mul_hi_u32 v0, v5, v0
	v_add_u32_e32 v0, v5, v0
	v_mul_hi_u32 v0, v6, v0
	v_mul_lo_u32 v4, v0, v3
	v_sub_u32_e32 v4, v6, v4
	v_add_u32_e32 v5, 1, v0
	v_cmp_ge_u32_e32 vcc, v4, v3
	s_nop 1
	v_cndmask_b32_e32 v0, v0, v5, vcc
	v_sub_u32_e32 v5, v4, v3
	v_cndmask_b32_e32 v4, v4, v5, vcc
	v_add_u32_e32 v5, 1, v0
	v_cmp_ge_u32_e32 vcc, v4, v3
	v_add_u32_e32 v4, 1, v6
	s_nop 0
	v_cndmask_b32_e32 v0, v0, v5, vcc
	v_mul_lo_u32 v5, v3, v0
	v_add_u32_e32 v3, v5, v3
	v_cmp_ne_u32_e32 vcc, v4, v3
	s_and_saveexec_b64 s[16:17], vcc
	s_xor_b64 s[20:21], exec, s[16:17]
	s_cbranch_execz .LBB0_241
	v_readlane_b32 s16, v245, 18
	v_readlane_b32 s17, v245, 19
	s_waitcnt lgkmcnt(0)
	s_nop 3
	global_load_dword v2, v1, s[16:17] sc1
	s_waitcnt vmcnt(0)
	v_cmp_eq_u32_e32 vcc, v2, v0
	s_and_saveexec_b64 s[22:23], vcc
	s_cbranch_execz .LBB0_240
	s_mov_b32 s44, 1
	s_mov_b64 s[36:37], 0
	s_branch .LBB0_231

; __device__ __forceinline__ unsigned xb_ld(unsigned* p)              { return __hip_atomic_load(p, __ATOMIC_RELAXED, __HIP_MEMORY_SCOPE_AGENT); }
; __device__ __forceinline__ unsigned xb_add(unsigned* p, unsigned v) { return __hip_atomic_fetch_add(p, v, __ATOMIC_RELAXED, __HIP_MEMORY_SCOPE_AGENT); }
; #define XB_SPIN(cond, bar) do { unsigned _sp = 0; while (cond) { __builtin_amdgcn_s_sleep(1); \
;     if ((++_sp & 255u) == 0u) { if (xb_ld(&(bar)[XB_TMO])) break; if (_sp > XB_SPIN_CAP) { atomicAdd(&(bar)[XB_TMO], 1u); break; } } } } while (0)
; __device__ __forceinline__ void xcd_barrier(const XcdBarrier& b) {
;     ...
;         unsigned nloc = b.st[0], nx = b.st[1];
;         if (nloc == 0u) { xcd_barrier_complete(bar, b.x, nloc, nx); b.st[0] = nloc; b.st[1] = nx; }
;         const unsigned old = xb_add(&bar[XB_XSUB(b.x)], 1u);
;         const unsigned gen = old / nloc;
;         if (old + 1u == (gen + 1u) * nloc) {
;             __builtin_amdgcn_fence(__ATOMIC_RELEASE, "agent");
;             asm volatile("s_waitcnt vmcnt(0)" ::: "memory");
;             const unsigned og = xb_add(&bar[XB_TOP], 1u);
;             const unsigned tg = og / nx;
;             if (og + 1u == (tg + 1u) * nx) xb_add(&bar[XB_TOPGEN], 1u);
;             else XB_SPIN(xb_ld(&bar[XB_TOPGEN]) == tg, bar);
;             __builtin_amdgcn_fence(__ATOMIC_ACQUIRE, "agent");
;             xb_add(&bar[XB_XGEN(b.x)], 1u);
;             asm volatile("s_waitcnt vmcnt(0)" ::: "memory");
;         } else {
;             XB_SPIN(xb_ld(&bar[XB_XGEN(b.x)]) == gen, bar);
.LBB0_396:
	s_or_b64 exec, exec, s[16:17]
	buffer_inv sc1
	v_cvt_f32_u32_e32 v5, v3
	s_waitcnt vmcnt(1)
	v_readfirstlane_b32 s16, v4
	v_sub_u32_e32 v4, 0, v3
	v_rcp_iflag_f32_e32 v5, v5
	v_add_u32_e32 v6, s16, v0
	v_mul_f32_e32 v5, 0x4f7ffffe, v5
	v_cvt_u32_f32_e32 v5, v5
	v_mul_lo_u32 v0, v4, v5
	v_mul_hi_u32 v0, v5, v0
	v_add_u32_e32 v0, v5, v0
	v_mul_hi_u32 v0, v6, v0
	v_mul_lo_u32 v4, v0, v3
	v_sub_u32_e32 v4, v6, v4
	v_add_u32_e32 v5, 1, v0
	v_cmp_ge_u32_e32 vcc, v4, v3
	s_nop 1
	v_cndmask_b32_e32 v0, v0, v5, vcc
	v_sub_u32_e32 v5, v4, v3
	v_cndmask_b32_e32 v4, v4, v5, vcc
	v_add_u32_e32 v5, 1, v0
	v_cmp_ge_u32_e32 vcc, v4, v3
	v_add_u32_e32 v4, 1, v6
	s_nop 0
	v_cndmask_b32_e32 v0, v0, v5, vcc
	v_mul_lo_u32 v5, v3, v0
	v_add_u32_e32 v3, v5, v3
	v_cmp_ne_u32_e32 vcc, v4, v3
	s_and_saveexec_b64 s[16:17], vcc
	s_xor_b64 s[36:37], exec, s[16:17]
	s_cbranch_execz .LBB0_410
	v_readlane_b32 s16, v245, 18
	v_readlane_b32 s17, v245, 19
	s_waitcnt lgkmcnt(0)
	s_nop 3
	global_load_dword v2, v1, s[16:17] sc1
	s_waitcnt vmcnt(0)
	v_cmp_eq_u32_e32 vcc, v2, v0
	s_and_saveexec_b64 s[38:39], vcc
	s_cbranch_execz .LBB0_409
	s_mov_b32 s23, 1
	s_mov_b64 s[40:41], 0
	s_branch .LBB0_400

; __device__ __forceinline__ unsigned xb_ld(unsigned* p)              { return __hip_atomic_load(p, __ATOMIC_RELAXED, __HIP_MEMORY_SCOPE_AGENT); }
; __device__ __forceinline__ unsigned xb_add(unsigned* p, unsigned v) { return __hip_atomic_fetch_add(p, v, __ATOMIC_RELAXED, __HIP_MEMORY_SCOPE_AGENT); }
; #define XB_SPIN(cond, bar) do { unsigned _sp = 0; while (cond) { __builtin_amdgcn_s_sleep(1); \
;     if ((++_sp & 255u) == 0u) { if (xb_ld(&(bar)[XB_TMO])) break; if (_sp > XB_SPIN_CAP) { atomicAdd(&(bar)[XB_TMO], 1u); break; } } } } while (0)
; __device__ __forceinline__ void xcd_barrier(const XcdBarrier& b) {
;     ...
;         unsigned nloc = b.st[0], nx = b.st[1];
;         if (nloc == 0u) { xcd_barrier_complete(bar, b.x, nloc, nx); b.st[0] = nloc; b.st[1] = nx; }
;         const unsigned old = xb_add(&bar[XB_XSUB(b.x)], 1u);
;         const unsigned gen = old / nloc;
;         if (old + 1u == (gen + 1u) * nloc) {
;             __builtin_amdgcn_fence(__ATOMIC_RELEASE, "agent");
;             asm volatile("s_waitcnt vmcnt(0)" ::: "memory");
;             const unsigned og = xb_add(&bar[XB_TOP], 1u);
;             const unsigned tg = og / nx;
;             if (og + 1u == (tg + 1u) * nx) xb_add(&bar[XB_TOPGEN], 1u);
;             else XB_SPIN(xb_ld(&bar[XB_TOPGEN]) == tg, bar);
;             __builtin_amdgcn_fence(__ATOMIC_ACQUIRE, "agent");
;             xb_add(&bar[XB_XGEN(b.x)], 1u);
;             asm volatile("s_waitcnt vmcnt(0)" ::: "memory");
;         } else {
;             XB_SPIN(xb_ld(&bar[XB_XGEN(b.x)]) == gen, bar);
.LBB0_537:
	s_or_b64 exec, exec, s[16:17]
	buffer_inv sc1
	v_cvt_f32_u32_e32 v5, v3
	s_waitcnt vmcnt(1)
	v_readfirstlane_b32 s16, v4
	v_sub_u32_e32 v4, 0, v3
	v_rcp_iflag_f32_e32 v5, v5
	v_add_u32_e32 v6, s16, v0
	v_mul_f32_e32 v5, 0x4f7ffffe, v5
	v_cvt_u32_f32_e32 v5, v5
	v_mul_lo_u32 v0, v4, v5
	v_mul_hi_u32 v0, v5, v0
	v_add_u32_e32 v0, v5, v0
	v_mul_hi_u32 v0, v6, v0
	v_mul_lo_u32 v4, v0, v3
	v_sub_u32_e32 v4, v6, v4
	v_add_u32_e32 v5, 1, v0
	v_cmp_ge_u32_e32 vcc, v4, v3
	s_nop 1
	v_cndmask_b32_e32 v0, v0, v5, vcc
	v_sub_u32_e32 v5, v4, v3
	v_cndmask_b32_e32 v4, v4, v5, vcc
	v_add_u32_e32 v5, 1, v0
	v_cmp_ge_u32_e32 vcc, v4, v3
	v_add_u32_e32 v4, 1, v6
	s_nop 0
	v_cndmask_b32_e32 v0, v0, v5, vcc
	v_mul_lo_u32 v5, v3, v0
	v_add_u32_e32 v3, v5, v3
	v_cmp_ne_u32_e32 vcc, v4, v3
	s_and_saveexec_b64 s[16:17], vcc
	s_xor_b64 s[36:37], exec, s[16:17]
	s_cbranch_execz .LBB0_551
	v_readlane_b32 s16, v245, 18
	v_readlane_b32 s17, v245, 19
	s_waitcnt lgkmcnt(0)
	s_nop 3
	global_load_dword v2, v1, s[16:17] sc1
	s_waitcnt vmcnt(0)
	v_cmp_eq_u32_e32 vcc, v2, v0
	s_and_saveexec_b64 s[40:41], vcc
	s_cbranch_execz .LBB0_550
	s_mov_b32 s23, 1
	s_mov_b64 s[42:43], 0
	s_branch .LBB0_541

; __device__ __forceinline__ unsigned xb_ld(unsigned* p)              { return __hip_atomic_load(p, __ATOMIC_RELAXED, __HIP_MEMORY_SCOPE_AGENT); }
; __device__ __forceinline__ unsigned xb_add(unsigned* p, unsigned v) { return __hip_atomic_fetch_add(p, v, __ATOMIC_RELAXED, __HIP_MEMORY_SCOPE_AGENT); }
; #define XB_SPIN(cond, bar) do { unsigned _sp = 0; while (cond) { __builtin_amdgcn_s_sleep(1); \
;     if ((++_sp & 255u) == 0u) { if (xb_ld(&(bar)[XB_TMO])) break; if (_sp > XB_SPIN_CAP) { atomicAdd(&(bar)[XB_TMO], 1u); break; } } } } while (0)
; __device__ __forceinline__ void xcd_barrier(const XcdBarrier& b) {
;     ...
;         unsigned nloc = b.st[0], nx = b.st[1];
;         if (nloc == 0u) { xcd_barrier_complete(bar, b.x, nloc, nx); b.st[0] = nloc; b.st[1] = nx; }
;         const unsigned old = xb_add(&bar[XB_XSUB(b.x)], 1u);
;         const unsigned gen = old / nloc;
;         if (old + 1u == (gen + 1u) * nloc) {
;             __builtin_amdgcn_fence(__ATOMIC_RELEASE, "agent");
;             asm volatile("s_waitcnt vmcnt(0)" ::: "memory");
;             const unsigned og = xb_add(&bar[XB_TOP], 1u);
;             const unsigned tg = og / nx;
;             if (og + 1u == (tg + 1u) * nx) xb_add(&bar[XB_TOPGEN], 1u);
;             else XB_SPIN(xb_ld(&bar[XB_TOPGEN]) == tg, bar);
;             __builtin_amdgcn_fence(__ATOMIC_ACQUIRE, "agent");
;             xb_add(&bar[XB_XGEN(b.x)], 1u);
;             asm volatile("s_waitcnt vmcnt(0)" ::: "memory");
;         } else {
;             XB_SPIN(xb_ld(&bar[XB_XGEN(b.x)]) == gen, bar);
.LBB0_752:
	s_or_b64 exec, exec, s[16:17]
	buffer_inv sc1
	v_cvt_f32_u32_e32 v5, v3
	s_waitcnt vmcnt(1)
	v_readfirstlane_b32 s16, v4
	v_sub_u32_e32 v4, 0, v3
	v_rcp_iflag_f32_e32 v5, v5
	v_add_u32_e32 v6, s16, v0
	v_mul_f32_e32 v5, 0x4f7ffffe, v5
	v_cvt_u32_f32_e32 v5, v5
	v_mul_lo_u32 v0, v4, v5
	v_mul_hi_u32 v0, v5, v0
	v_add_u32_e32 v0, v5, v0
	v_mul_hi_u32 v0, v6, v0
	v_mul_lo_u32 v4, v0, v3
	v_sub_u32_e32 v4, v6, v4
	v_add_u32_e32 v5, 1, v0
	v_cmp_ge_u32_e32 vcc, v4, v3
	s_nop 1
	v_cndmask_b32_e32 v0, v0, v5, vcc
	v_sub_u32_e32 v5, v4, v3
	v_cndmask_b32_e32 v4, v4, v5, vcc
	v_add_u32_e32 v5, 1, v0
	v_cmp_ge_u32_e32 vcc, v4, v3
	v_add_u32_e32 v4, 1, v6
	s_nop 0
	v_cndmask_b32_e32 v0, v0, v5, vcc
	v_mul_lo_u32 v5, v3, v0
	v_add_u32_e32 v3, v5, v3
	v_cmp_ne_u32_e32 vcc, v4, v3
	s_and_saveexec_b64 s[16:17], vcc
	s_xor_b64 s[18:19], exec, s[16:17]
	s_cbranch_execz .LBB0_766
	v_readlane_b32 s16, v245, 18
	v_readlane_b32 s17, v245, 19
	s_waitcnt lgkmcnt(0)
	s_nop 3
	global_load_dword v2, v1, s[16:17] sc1
	s_waitcnt vmcnt(0)
	v_cmp_eq_u32_e32 vcc, v2, v0
	s_and_saveexec_b64 s[20:21], vcc
	s_cbranch_execz .LBB0_765
	s_mov_b32 s42, 1
	s_mov_b64 s[22:23], 0
	s_branch .LBB0_756
